# SWA inner loop: the 24-state s_nop pad and the s_nop 0 pads in front of the row-max chain deleted (the ALiBi VALU block already sits between the QK MFMAs and the first read of their result)
# baseline (speedup 1.0000x reference)
.LBB0_579:
	v_max3_f32 v0, v34, v35, v50
	v_max3_f32 v99, v36, v37, v51
	v_max3_f32 v0, v0, v52, v53
	v_max3_f32 v99, v99, v40, v41
	v_max3_f32 v0, v0, v38, v39
	v_max3_f32 v99, v99, v56, v57
	v_max3_f32 v0, v0, v54, v55
	v_max3_f32 v99, v99, v44, v45
	v_max3_f32 v0, v0, v42, v43
	v_max3_f32 v99, v99, v60, v61
	v_max3_f32 v0, v0, v58, v59
	v_max3_f32 v99, v99, v48, v49
	v_max3_f32 v0, v0, v46, v47
	v_max3_f32 v99, v99, v64, v65
	v_max3_f32 v0, v0, v62, v63
	v_max_f32_e32 v99, v99, v99
	v_max_f32_e32 v0, v0, v0
	v_max_f32_e32 v0, v0, v99
	v_mov_b32_e32 v99, v0
	s_nop 1
	v_permlane32_swap_b32_e32 v0, v99
	v_max_f32_e32 v99, v99, v99
	v_max_f32_e32 v0, v0, v0
	v_max_f32_e32 v0, v0, v99
	v_add_f32_e32 v99, 0x41000000, v130
	v_cmp_gt_f32_e32 vcc, v0, v99
	s_cbranch_vccz .LBB0_581
	v_max_f32_e32 v0, v0, v0
	v_max_f32_e32 v99, v130, v130
	v_max_f32_e32 v99, v99, v0
	v_sub_f32_e32 v0, v130, v99
	v_exp_f32_e32 v0, v0
	v_mov_b32_e32 v130, v99
	v_mul_f32_e32 v107, v107, v0
	v_pk_mul_f32 v[32:33], v[32:33], v[0:1] op_sel_hi:[1,0]
	v_pk_mul_f32 v[30:31], v[30:31], v[0:1] op_sel_hi:[1,0]
	v_pk_mul_f32 v[28:29], v[28:29], v[0:1] op_sel_hi:[1,0]
	v_pk_mul_f32 v[26:27], v[26:27], v[0:1] op_sel_hi:[1,0]
	v_pk_mul_f32 v[24:25], v[24:25], v[0:1] op_sel_hi:[1,0]
	v_pk_mul_f32 v[22:23], v[22:23], v[0:1] op_sel_hi:[1,0]
	v_pk_mul_f32 v[20:21], v[20:21], v[0:1] op_sel_hi:[1,0]
	v_pk_mul_f32 v[18:19], v[18:19], v[0:1] op_sel_hi:[1,0]
	v_pk_mul_f32 v[16:17], v[16:17], v[0:1] op_sel_hi:[1,0]
	v_pk_mul_f32 v[14:15], v[14:15], v[0:1] op_sel_hi:[1,0]
	v_pk_mul_f32 v[12:13], v[12:13], v[0:1] op_sel_hi:[1,0]
	v_pk_mul_f32 v[10:11], v[10:11], v[0:1] op_sel_hi:[1,0]
	v_pk_mul_f32 v[8:9], v[8:9], v[0:1] op_sel_hi:[1,0]
	v_pk_mul_f32 v[6:7], v[6:7], v[0:1] op_sel_hi:[1,0]
	v_pk_mul_f32 v[4:5], v[4:5], v[0:1] op_sel_hi:[1,0]
	v_pk_mul_f32 v[2:3], v[2:3], v[0:1] op_sel_hi:[1,0]
